# MLA softmax blocks (4 sites): row sum of the 32 exps by 15 packed adds + 2 adds instead of 29 add instructions (exps written to spare adjacent VGPR pairs); same exps, packs and P.V cluster; address-pr
# baseline (speedup 1.0000x reference)
.LBB0_367:
	v_exp_f32_e32 v218, v80
	v_exp_f32_e32 v219, v81
	v_exp_f32_e32 v220, v82
	v_exp_f32_e32 v221, v83
	v_exp_f32_e32 v222, v84
	v_exp_f32_e32 v223, v85
	v_exp_f32_e32 v224, v86
	v_exp_f32_e32 v225, v87
	v_cvt_pk_bf16_f32 v8, v218, v219
	v_cvt_pk_bf16_f32 v9, v220, v221
	v_cvt_pk_bf16_f32 v10, v222, v223
	v_cvt_pk_bf16_f32 v11, v224, v225
	v_pk_add_f32 v[226:227], v[218:219], v[220:221]
	v_pk_add_f32 v[226:227], v[226:227], v[222:223]
	v_pk_add_f32 v[226:227], v[226:227], v[224:225]
	v_exp_f32_e32 v218, v88
	v_exp_f32_e32 v219, v89
	v_exp_f32_e32 v220, v90
	v_exp_f32_e32 v221, v91
	v_exp_f32_e32 v222, v92
	v_exp_f32_e32 v223, v93
	v_exp_f32_e32 v224, v94
	v_exp_f32_e32 v225, v95
	v_cvt_pk_bf16_f32 v18, v218, v219
	v_cvt_pk_bf16_f32 v19, v220, v221
	v_cvt_pk_bf16_f32 v20, v222, v223
	v_cvt_pk_bf16_f32 v21, v224, v225
	v_pk_add_f32 v[226:227], v[226:227], v[218:219]
	v_pk_add_f32 v[226:227], v[226:227], v[220:221]
	v_pk_add_f32 v[226:227], v[226:227], v[222:223]
	v_pk_add_f32 v[226:227], v[226:227], v[224:225]
	v_exp_f32_e32 v218, v96
	v_exp_f32_e32 v219, v97
	v_exp_f32_e32 v220, v98
	v_exp_f32_e32 v221, v99
	v_exp_f32_e32 v222, v100
	v_exp_f32_e32 v223, v101
	v_exp_f32_e32 v224, v102
	v_exp_f32_e32 v225, v103
	v_cvt_pk_bf16_f32 v12, v218, v219
	v_cvt_pk_bf16_f32 v13, v220, v221
	v_cvt_pk_bf16_f32 v14, v222, v223
	v_cvt_pk_bf16_f32 v15, v224, v225
	v_pk_add_f32 v[226:227], v[226:227], v[218:219]
	v_pk_add_f32 v[226:227], v[226:227], v[220:221]
	v_pk_add_f32 v[226:227], v[226:227], v[222:223]
	v_pk_add_f32 v[226:227], v[226:227], v[224:225]
	v_exp_f32_e32 v218, v104
	v_exp_f32_e32 v219, v105
	v_exp_f32_e32 v220, v106
	v_exp_f32_e32 v221, v107
	v_exp_f32_e32 v222, v108
	v_exp_f32_e32 v223, v109
	v_exp_f32_e32 v224, v110
	v_exp_f32_e32 v225, v111
	v_cvt_pk_bf16_f32 v22, v218, v219
	v_cvt_pk_bf16_f32 v23, v220, v221
	v_cvt_pk_bf16_f32 v24, v222, v223
	v_cvt_pk_bf16_f32 v25, v224, v225
	v_pk_add_f32 v[226:227], v[226:227], v[218:219]
	v_pk_add_f32 v[226:227], v[226:227], v[220:221]
	v_pk_add_f32 v[226:227], v[226:227], v[222:223]
	v_pk_add_f32 v[226:227], v[226:227], v[224:225]
	ds_read_b64_tr_b16 v[26:27], v2 offset:61440
	ds_read_b64_tr_b16 v[28:29], v2 offset:61952
	v_add_u32_e32 v0, 0xd000, v2
	ds_read_b64_tr_b16 v[80:81], v2 offset:62464
	ds_read_b64_tr_b16 v[82:83], v2 offset:62976
	s_waitcnt lgkmcnt(2)
	v_mfma_f32_32x32x16_bf16 v[48:63], v[26:29], v[8:11], v[48:63]
	ds_read_b64_tr_b16 v[26:27], v0 offset:12288
	ds_read_b64_tr_b16 v[28:29], v0 offset:12800
	ds_read_b64_tr_b16 v[84:85], v0 offset:13312
	ds_read_b64_tr_b16 v[86:87], v0 offset:13824
	s_waitcnt lgkmcnt(2)
	v_mfma_f32_32x32x16_bf16 v[32:47], v[26:29], v[8:11], v[32:47]
	v_mfma_f32_32x32x16_bf16 v[48:63], v[80:83], v[18:21], v[48:63]
	s_waitcnt lgkmcnt(0)
	v_mfma_f32_32x32x16_bf16 v[32:47], v[84:87], v[18:21], v[32:47]
	ds_read_b64_tr_b16 v[8:9], v2 offset:63488
	ds_read_b64_tr_b16 v[10:11], v2 offset:64000
	ds_read_b64_tr_b16 v[18:19], v2 offset:64512
	ds_read_b64_tr_b16 v[20:21], v2 offset:65024
	s_waitcnt lgkmcnt(2)
	v_mfma_f32_32x32x16_bf16 v[48:63], v[8:11], v[12:15], v[48:63]
	ds_read_b64_tr_b16 v[2:3], v0 offset:14336
	ds_read_b64_tr_b16 v[4:5], v0 offset:14848
	ds_read_b64_tr_b16 v[8:9], v0 offset:15360
	ds_read_b64_tr_b16 v[10:11], v0 offset:15872
	s_waitcnt lgkmcnt(2)
	v_mfma_f32_32x32x16_bf16 v[32:47], v[2:5], v[12:15], v[32:47]
	v_mfma_f32_32x32x16_bf16 v[48:63], v[18:21], v[22:25], v[48:63]
	s_waitcnt lgkmcnt(0)
	v_mfma_f32_32x32x16_bf16 v[32:47], v[8:11], v[22:25], v[32:47]
	v_add_f32_e32 v228, v226, v227
	v_add_f32_e32 v6, v6, v228
	s_andn2_b64 vcc, exec, s[4:5]
	s_cbranch_vccnz .LBB0_350
	s_branch .LBB0_374
	s_nop 0
	s_nop 0
	s_nop 0
	s_nop 0
	s_nop 0
	s_nop 0
	s_nop 0
	s_nop 0
	s_nop 0
	s_nop 0
	s_nop 0

.LBB0_372:
	v_exp_f32_e32 v218, v80
	v_exp_f32_e32 v219, v81
	v_exp_f32_e32 v220, v82
	v_exp_f32_e32 v221, v83
	v_exp_f32_e32 v222, v84
	v_exp_f32_e32 v223, v85
	v_exp_f32_e32 v224, v86
	v_exp_f32_e32 v225, v87
	v_cvt_pk_bf16_f32 v8, v218, v219
	v_cvt_pk_bf16_f32 v9, v220, v221
	v_cvt_pk_bf16_f32 v10, v222, v223
	v_cvt_pk_bf16_f32 v11, v224, v225
	v_pk_add_f32 v[226:227], v[218:219], v[220:221]
	v_pk_add_f32 v[226:227], v[226:227], v[222:223]
	v_pk_add_f32 v[226:227], v[226:227], v[224:225]
	v_exp_f32_e32 v218, v88
	v_exp_f32_e32 v219, v89
	v_exp_f32_e32 v220, v90
	v_exp_f32_e32 v221, v91
	v_exp_f32_e32 v222, v92
	v_exp_f32_e32 v223, v93
	v_exp_f32_e32 v224, v94
	v_exp_f32_e32 v225, v95
	v_cvt_pk_bf16_f32 v18, v218, v219
	v_cvt_pk_bf16_f32 v19, v220, v221
	v_cvt_pk_bf16_f32 v20, v222, v223
	v_cvt_pk_bf16_f32 v21, v224, v225
	v_pk_add_f32 v[226:227], v[226:227], v[218:219]
	v_pk_add_f32 v[226:227], v[226:227], v[220:221]
	v_pk_add_f32 v[226:227], v[226:227], v[222:223]
	v_pk_add_f32 v[226:227], v[226:227], v[224:225]
	v_exp_f32_e32 v218, v96
	v_exp_f32_e32 v219, v97
	v_exp_f32_e32 v220, v98
	v_exp_f32_e32 v221, v99
	v_exp_f32_e32 v222, v100
	v_exp_f32_e32 v223, v101
	v_exp_f32_e32 v224, v102
	v_exp_f32_e32 v225, v103
	v_cvt_pk_bf16_f32 v12, v218, v219
	v_cvt_pk_bf16_f32 v13, v220, v221
	v_cvt_pk_bf16_f32 v14, v222, v223
	v_cvt_pk_bf16_f32 v15, v224, v225
	v_pk_add_f32 v[226:227], v[226:227], v[218:219]
	v_pk_add_f32 v[226:227], v[226:227], v[220:221]
	v_pk_add_f32 v[226:227], v[226:227], v[222:223]
	v_pk_add_f32 v[226:227], v[226:227], v[224:225]
	v_exp_f32_e32 v218, v104
	v_exp_f32_e32 v219, v105
	v_exp_f32_e32 v220, v106
	v_exp_f32_e32 v221, v107
	v_exp_f32_e32 v222, v108
	v_exp_f32_e32 v223, v109
	v_exp_f32_e32 v224, v110
	v_exp_f32_e32 v225, v111
	v_cvt_pk_bf16_f32 v22, v218, v219
	v_cvt_pk_bf16_f32 v23, v220, v221
	v_cvt_pk_bf16_f32 v24, v222, v223
	v_cvt_pk_bf16_f32 v25, v224, v225
	v_pk_add_f32 v[226:227], v[226:227], v[218:219]
	v_pk_add_f32 v[226:227], v[226:227], v[220:221]
	v_pk_add_f32 v[226:227], v[226:227], v[222:223]
	v_pk_add_f32 v[226:227], v[226:227], v[224:225]
	ds_read_b64_tr_b16 v[26:27], v2 offset:53248
	ds_read_b64_tr_b16 v[28:29], v2 offset:53760
	ds_read_b64_tr_b16 v[80:81], v2 offset:54272
	ds_read_b64_tr_b16 v[82:83], v2 offset:54784
	s_waitcnt lgkmcnt(2)
	v_mfma_f32_32x32x16_bf16 v[48:63], v[26:29], v[8:11], v[48:63]
	ds_read_b64_tr_b16 v[26:27], v2 offset:57344
	ds_read_b64_tr_b16 v[28:29], v2 offset:57856
	ds_read_b64_tr_b16 v[84:85], v2 offset:58368
	ds_read_b64_tr_b16 v[86:87], v2 offset:58880
	s_waitcnt lgkmcnt(2)
	v_mfma_f32_32x32x16_bf16 v[32:47], v[26:29], v[8:11], v[32:47]
	v_mfma_f32_32x32x16_bf16 v[48:63], v[80:83], v[18:21], v[48:63]
	s_waitcnt lgkmcnt(0)
	v_mfma_f32_32x32x16_bf16 v[32:47], v[84:87], v[18:21], v[32:47]
	ds_read_b64_tr_b16 v[8:9], v2 offset:55296
	ds_read_b64_tr_b16 v[10:11], v2 offset:55808
	ds_read_b64_tr_b16 v[18:19], v2 offset:56320
	ds_read_b64_tr_b16 v[20:21], v2 offset:56832
	s_waitcnt lgkmcnt(2)
	v_mfma_f32_32x32x16_bf16 v[48:63], v[8:11], v[12:15], v[48:63]
	ds_read_b64_tr_b16 v[8:9], v2 offset:59392
	ds_read_b64_tr_b16 v[10:11], v2 offset:59904
	ds_read_b64_tr_b16 v[26:27], v2 offset:60416
	ds_read_b64_tr_b16 v[28:29], v2 offset:60928
	s_waitcnt lgkmcnt(2)
	v_mfma_f32_32x32x16_bf16 v[32:47], v[8:11], v[12:15], v[32:47]
	v_mfma_f32_32x32x16_bf16 v[48:63], v[18:21], v[22:25], v[48:63]
	s_waitcnt lgkmcnt(0)
	v_mfma_f32_32x32x16_bf16 v[32:47], v[26:29], v[22:25], v[32:47]
	v_add_f32_e32 v228, v226, v227
	v_add_f32_e32 v6, v6, v228
	s_add_i32 s2, s57, 64
	s_cmp_gt_i32 s2, s54
	s_cbranch_scc0 .LBB0_363

.LBB0_376:
	s_andn2_saveexec_b64 s[4:5], s[4:5]
	s_cbranch_execz .LBB0_349
	v_add3_u32 v2, s2, v174, v176
	s_add_i32 s2, s2, s3
	ds_write_b128 v2, v[144:147] offset:128
	s_waitcnt vmcnt(1)
	ds_write_b128 v0, v[152:155] offset:13312
	v_add_u32_e32 v0, s2, v170
	v_add3_u32 v0, v0, v171, v172
	s_waitcnt vmcnt(0)
	ds_write_b128 v0, v[156:159] offset:61440
	ds_write_b128 v2, v[148:151] offset:13440
	s_branch .LBB0_349
	s_nop 0
	s_nop 0
	s_nop 0
	s_nop 0
	s_nop 0
	s_nop 0
	s_nop 0
	s_nop 0
	s_nop 0
	s_nop 0

.LBB0_410:
	v_exp_f32_e32 v218, v80
	v_exp_f32_e32 v219, v81
	v_exp_f32_e32 v220, v82
	v_exp_f32_e32 v221, v83
	v_exp_f32_e32 v222, v84
	v_exp_f32_e32 v223, v85
	v_exp_f32_e32 v224, v86
	v_exp_f32_e32 v225, v87
	v_cvt_pk_bf16_f32 v8, v218, v219
	v_cvt_pk_bf16_f32 v9, v220, v221
	v_cvt_pk_bf16_f32 v10, v222, v223
	v_cvt_pk_bf16_f32 v11, v224, v225
	v_pk_add_f32 v[226:227], v[218:219], v[220:221]
	v_pk_add_f32 v[226:227], v[226:227], v[222:223]
	v_pk_add_f32 v[226:227], v[226:227], v[224:225]
	v_exp_f32_e32 v218, v88
	v_exp_f32_e32 v219, v89
	v_exp_f32_e32 v220, v90
	v_exp_f32_e32 v221, v91
	v_exp_f32_e32 v222, v92
	v_exp_f32_e32 v223, v93
	v_exp_f32_e32 v224, v94
	v_exp_f32_e32 v225, v95
	v_cvt_pk_bf16_f32 v18, v218, v219
	v_cvt_pk_bf16_f32 v19, v220, v221
	v_cvt_pk_bf16_f32 v20, v222, v223
	v_cvt_pk_bf16_f32 v21, v224, v225
	v_pk_add_f32 v[226:227], v[226:227], v[218:219]
	v_pk_add_f32 v[226:227], v[226:227], v[220:221]
	v_pk_add_f32 v[226:227], v[226:227], v[222:223]
	v_pk_add_f32 v[226:227], v[226:227], v[224:225]
	v_exp_f32_e32 v218, v96
	v_exp_f32_e32 v219, v97
	v_exp_f32_e32 v220, v98
	v_exp_f32_e32 v221, v99
	v_exp_f32_e32 v222, v100
	v_exp_f32_e32 v223, v101
	v_exp_f32_e32 v224, v102
	v_exp_f32_e32 v225, v103
	v_cvt_pk_bf16_f32 v12, v218, v219
	v_cvt_pk_bf16_f32 v13, v220, v221
	v_cvt_pk_bf16_f32 v14, v222, v223
	v_cvt_pk_bf16_f32 v15, v224, v225
	v_pk_add_f32 v[226:227], v[226:227], v[218:219]
	v_pk_add_f32 v[226:227], v[226:227], v[220:221]
	v_pk_add_f32 v[226:227], v[226:227], v[222:223]
	v_pk_add_f32 v[226:227], v[226:227], v[224:225]
	v_exp_f32_e32 v218, v104
	v_exp_f32_e32 v219, v105
	v_exp_f32_e32 v220, v106
	v_exp_f32_e32 v221, v107
	v_exp_f32_e32 v222, v108
	v_exp_f32_e32 v223, v109
	v_exp_f32_e32 v224, v110
	v_exp_f32_e32 v225, v111
	v_cvt_pk_bf16_f32 v22, v218, v219
	v_cvt_pk_bf16_f32 v23, v220, v221
	v_cvt_pk_bf16_f32 v24, v222, v223
	v_cvt_pk_bf16_f32 v25, v224, v225
	v_pk_add_f32 v[226:227], v[226:227], v[218:219]
	v_pk_add_f32 v[226:227], v[226:227], v[220:221]
	v_pk_add_f32 v[226:227], v[226:227], v[222:223]
	v_pk_add_f32 v[226:227], v[226:227], v[224:225]
	ds_read_b64_tr_b16 v[26:27], v2 offset:53248
	ds_read_b64_tr_b16 v[28:29], v2 offset:53760
	ds_read_b64_tr_b16 v[80:81], v2 offset:54272
	ds_read_b64_tr_b16 v[82:83], v2 offset:54784
	s_waitcnt lgkmcnt(2)
	v_mfma_f32_32x32x16_bf16 v[48:63], v[26:29], v[8:11], v[48:63]
	ds_read_b64_tr_b16 v[26:27], v2 offset:57344
	ds_read_b64_tr_b16 v[28:29], v2 offset:57856
	ds_read_b64_tr_b16 v[84:85], v2 offset:58368
	ds_read_b64_tr_b16 v[86:87], v2 offset:58880
	s_waitcnt lgkmcnt(2)
	v_mfma_f32_32x32x16_bf16 v[32:47], v[26:29], v[8:11], v[32:47]
	v_mfma_f32_32x32x16_bf16 v[48:63], v[80:83], v[18:21], v[48:63]
	s_waitcnt lgkmcnt(0)
	v_mfma_f32_32x32x16_bf16 v[32:47], v[84:87], v[18:21], v[32:47]
	ds_read_b64_tr_b16 v[8:9], v2 offset:55296
	ds_read_b64_tr_b16 v[10:11], v2 offset:55808
	ds_read_b64_tr_b16 v[18:19], v2 offset:56320
	ds_read_b64_tr_b16 v[20:21], v2 offset:56832
	s_waitcnt lgkmcnt(2)
	v_mfma_f32_32x32x16_bf16 v[48:63], v[8:11], v[12:15], v[48:63]
	ds_read_b64_tr_b16 v[8:9], v2 offset:59392
	ds_read_b64_tr_b16 v[10:11], v2 offset:59904
	ds_read_b64_tr_b16 v[26:27], v2 offset:60416
	ds_read_b64_tr_b16 v[28:29], v2 offset:60928
	s_waitcnt lgkmcnt(2)
	v_mfma_f32_32x32x16_bf16 v[32:47], v[8:11], v[12:15], v[32:47]
	v_mfma_f32_32x32x16_bf16 v[48:63], v[18:21], v[22:25], v[48:63]
	s_waitcnt lgkmcnt(0)
	v_mfma_f32_32x32x16_bf16 v[32:47], v[26:29], v[22:25], v[32:47]
	v_add_f32_e32 v228, v226, v227
	v_add_f32_e32 v6, v6, v228
	s_add_i32 s2, s37, 64
	s_cmp_gt_i32 s2, s28
	s_cbranch_scc0 .LBB0_401
